# grid barrier: members and XCD leaders poll the top-level arrival counter (TOP >= (k+1)*nx) directly instead of the generation word written afterwards by the last XCD leader
# speedup vs baseline: 1.0103x; 1.0043x over previous
; __device__ __forceinline__ unsigned xb_ld(unsigned* p)              { return __hip_atomic_load(p, __ATOMIC_RELAXED, __HIP_MEMORY_SCOPE_AGENT); }
; __device__ __forceinline__ unsigned xb_add(unsigned* p, unsigned v) { return __hip_atomic_fetch_add(p, v, __ATOMIC_RELAXED, __HIP_MEMORY_SCOPE_AGENT); }
; #define XB_SPIN(cond, bar) do { unsigned _sp = 0; while (cond) { __builtin_amdgcn_s_sleep(1); \
;     if ((++_sp & 255u) == 0u) { if (xb_ld(&(bar)[XB_TMO])) break; if (_sp > XB_SPIN_CAP) { atomicAdd(&(bar)[XB_TMO], 1u); break; } } } } while (0)
; __device__ __forceinline__ void xcd_barrier(const XcdBarrier& b, bool leader) {
;     ...
;         if (nloc == 0u) { xcd_barrier_complete(bar, b.x, nloc, nx); b.st[0] = nloc; b.st[1] = nx; }
;         const unsigned old = xb_add(&bar[XB_XSUB(b.x)], 1u);
;         const unsigned gen = old / nloc;
;         if (old + 1u == (gen + 1u) * nloc) {
;             __builtin_amdgcn_fence(__ATOMIC_RELEASE, "agent");
;             asm volatile("s_waitcnt vmcnt(0)" ::: "memory");
;             const unsigned og = xb_add(&bar[XB_TOP], 1u);
;             const unsigned tg = og / nx;
;             if (og + 1u == (tg + 1u) * nx) xb_add(&bar[XB_TOPGEN], 1u);
;             else XB_SPIN(xb_ld(&bar[XB_TOPGEN]) == tg, bar);
;             __builtin_amdgcn_fence(__ATOMIC_ACQUIRE, "agent");
;             xb_add(&bar[XB_XGEN(b.x)], 1u);
;             asm volatile("s_waitcnt vmcnt(0)" ::: "memory");
;         } else {
;             XB_SPIN(xb_ld(&bar[XB_XGEN(b.x)]) == gen, bar);
.LBB0_144:
	s_or_b64 exec, exec, s[10:11]
	v_cvt_f32_u32_e32 v4, v2
	s_waitcnt vmcnt(0)
	v_readfirstlane_b32 s8, v3
	v_sub_u32_e32 v3, 0, v2
	v_rcp_iflag_f32_e32 v4, v4
	v_add_u32_e32 v5, s8, v1
	v_mul_f32_e32 v4, 0x4f7ffffe, v4
	v_cvt_u32_f32_e32 v4, v4
	v_mul_lo_u32 v1, v3, v4
	v_mul_hi_u32 v1, v4, v1
	v_add_u32_e32 v1, v4, v1
	v_mul_hi_u32 v1, v5, v1
	v_mul_lo_u32 v3, v1, v2
	v_sub_u32_e32 v3, v5, v3
	v_add_u32_e32 v4, 1, v1
	v_cmp_ge_u32_e32 vcc, v3, v2
	s_nop 1
	v_cndmask_b32_e32 v1, v1, v4, vcc
	v_sub_u32_e32 v4, v3, v2
	v_cndmask_b32_e32 v3, v3, v4, vcc
	v_add_u32_e32 v4, 1, v1
	v_cmp_ge_u32_e32 vcc, v3, v2
	v_add_u32_e32 v3, 1, v5
	s_nop 0
	v_cndmask_b32_e32 v1, v1, v4, vcc
	v_mul_lo_u32 v4, v2, v1
	v_add_u32_e32 v2, v4, v2
	v_cmp_ne_u32_e32 vcc, v3, v2
	s_and_saveexec_b64 s[8:9], vcc
	s_xor_b64 s[8:9], exec, s[8:9]
	s_cbranch_execz .LBB0_158
	buffer_inv sc1
	s_waitcnt lgkmcnt(0)
	v_add_u32_e32 v1, 1, v1
	v_mul_lo_u32 v1, v1, v0
	v_mov_b32_e32 v0, 0x3000
	global_load_dword v0, v0, s[76:77] offset:1024 sc1
	s_add_u32 s14, s76, 0x3400
	s_addc_u32 s15, s77, 0
	s_waitcnt vmcnt(0)
	v_cmp_lt_u32_e32 vcc, v0, v1
	s_and_saveexec_b64 s[10:11], vcc
	s_cbranch_execz .LBB0_157
	s_mov_b32 s13, 1
	s_mov_b64 s[16:17], 0
	v_mov_b32_e32 v0, 0
	s_branch .LBB0_148

.LBB0_152:
	global_load_dword v2, v0, s[14:15] sc1
	s_add_i32 s13, s13, 1
	s_mov_b64 s[22:23], -1
	s_waitcnt vmcnt(0)
	v_cmp_ge_u32_e32 vcc, v2, v1
	s_orn2_b64 s[20:21], vcc, exec
	s_branch .LBB0_147

; __device__ __forceinline__ unsigned xb_ld(unsigned* p)              { return __hip_atomic_load(p, __ATOMIC_RELAXED, __HIP_MEMORY_SCOPE_AGENT); }
; __device__ __forceinline__ unsigned xb_add(unsigned* p, unsigned v) { return __hip_atomic_fetch_add(p, v, __ATOMIC_RELAXED, __HIP_MEMORY_SCOPE_AGENT); }
; #define XB_SPIN(cond, bar) do { unsigned _sp = 0; while (cond) { __builtin_amdgcn_s_sleep(1); \
;     if ((++_sp & 255u) == 0u) { if (xb_ld(&(bar)[XB_TMO])) break; if (_sp > XB_SPIN_CAP) { atomicAdd(&(bar)[XB_TMO], 1u); break; } } } } while (0)
; __device__ __forceinline__ void xcd_barrier(const XcdBarrier& b, bool leader) {
;     ...
;             const unsigned og = xb_add(&bar[XB_TOP], 1u);
;             const unsigned tg = og / nx;
;             if (og + 1u == (tg + 1u) * nx) xb_add(&bar[XB_TOPGEN], 1u);
;             else XB_SPIN(xb_ld(&bar[XB_TOPGEN]) == tg, bar);
.LBB0_161:
	s_or_b64 exec, exec, s[10:11]
	buffer_inv sc1
	v_cvt_f32_u32_e32 v3, v0
	s_waitcnt vmcnt(0)
	v_readfirstlane_b32 s8, v2
	s_add_u32 s10, s76, 0x3500
	s_addc_u32 s11, s77, 0
	v_rcp_iflag_f32_e32 v3, v3
	v_add_u32_e32 v1, s8, v1
	v_add_u32_e32 v4, 1, v1
	s_mov_b64 s[14:15], -1
	v_mul_f32_e32 v2, 0x4f7ffffe, v3
	v_cvt_u32_f32_e32 v2, v2
	v_sub_u32_e32 v3, 0, v0
	v_mul_lo_u32 v3, v3, v2
	v_mul_hi_u32 v3, v2, v3
	v_add_u32_e32 v2, v2, v3
	v_mul_hi_u32 v2, v1, v2
	v_mul_lo_u32 v3, v2, v0
	v_sub_u32_e32 v1, v1, v3
	v_add_u32_e32 v5, 1, v2
	v_cmp_ge_u32_e32 vcc, v1, v0
	v_sub_u32_e32 v3, v1, v0
	s_nop 0
	v_cndmask_b32_e32 v2, v2, v5, vcc
	v_cndmask_b32_e32 v1, v1, v3, vcc
	v_add_u32_e32 v3, 1, v2
	v_cmp_ge_u32_e32 vcc, v1, v0
	s_nop 1
	v_cndmask_b32_e32 v2, v2, v3, vcc
	v_mul_lo_u32 v1, v0, v2
	v_add_u32_e32 v0, v1, v0
	v_mov_b32_e32 v2, v0
	v_cmp_ne_u32_e32 vcc, v4, v0
	v_mov_b64_e32 v[0:1], s[10:11]
	s_and_saveexec_b64 s[8:9], vcc
	s_cbranch_execz .LBB0_173
	v_mov_b32_e32 v0, 0
	global_load_dword v1, v0, s[10:11] offset:-256 sc1
	s_mov_b64 s[18:19], 0
	s_waitcnt vmcnt(0)
	v_cmp_lt_u32_e32 vcc, v1, v2
	s_and_saveexec_b64 s[16:17], vcc
	s_cbranch_execz .LBB0_172
	s_add_u32 s14, s76, 0x200
	s_addc_u32 s15, s77, 0
	s_mov_b32 s13, 1
	s_branch .LBB0_165

; __device__ __forceinline__ unsigned xb_ld(unsigned* p)              { return __hip_atomic_load(p, __ATOMIC_RELAXED, __HIP_MEMORY_SCOPE_AGENT); }
; __device__ __forceinline__ unsigned xb_add(unsigned* p, unsigned v) { return __hip_atomic_fetch_add(p, v, __ATOMIC_RELAXED, __HIP_MEMORY_SCOPE_AGENT); }
; #define XB_SPIN(cond, bar) do { unsigned _sp = 0; while (cond) { __builtin_amdgcn_s_sleep(1); \
;     if ((++_sp & 255u) == 0u) { if (xb_ld(&(bar)[XB_TMO])) break; if (_sp > XB_SPIN_CAP) { atomicAdd(&(bar)[XB_TMO], 1u); break; } } } } while (0)
; __device__ __forceinline__ void xcd_barrier(const XcdBarrier& b, bool leader) {
;     ...
;             const unsigned og = xb_add(&bar[XB_TOP], 1u);
;             const unsigned tg = og / nx;
;             if (og + 1u == (tg + 1u) * nx) xb_add(&bar[XB_TOPGEN], 1u);
;             else XB_SPIN(xb_ld(&bar[XB_TOPGEN]) == tg, bar);
.LBB0_169:
	global_load_dword v1, v0, s[10:11] offset:-256 sc1
	s_add_i32 s13, s13, 1
	s_mov_b64 s[22:23], -1
	s_waitcnt vmcnt(0)
	v_cmp_ge_u32_e32 vcc, v1, v2
	s_orn2_b64 s[26:27], vcc, exec
	s_branch .LBB0_164

; __device__ __forceinline__ unsigned xb_ld(unsigned* p)              { return __hip_atomic_load(p, __ATOMIC_RELAXED, __HIP_MEMORY_SCOPE_AGENT); }
; __device__ __forceinline__ unsigned xb_add(unsigned* p, unsigned v) { return __hip_atomic_fetch_add(p, v, __ATOMIC_RELAXED, __HIP_MEMORY_SCOPE_AGENT); }
; #define XB_SPIN(cond, bar) do { unsigned _sp = 0; while (cond) { __builtin_amdgcn_s_sleep(1); \
;     if ((++_sp & 255u) == 0u) { if (xb_ld(&(bar)[XB_TMO])) break; if (_sp > XB_SPIN_CAP) { atomicAdd(&(bar)[XB_TMO], 1u); break; } } } } while (0)
; __device__ __forceinline__ void xcd_barrier(const XcdBarrier& b, bool leader) {
;     ...
;         const unsigned old = xb_add(&bar[XB_XSUB(b.x)], 1u);
;         const unsigned gen = old / nloc;
;         if (old + 1u == (gen + 1u) * nloc) {
;             __builtin_amdgcn_fence(__ATOMIC_RELEASE, "agent");
;             asm volatile("s_waitcnt vmcnt(0)" ::: "memory");
;             const unsigned og = xb_add(&bar[XB_TOP], 1u);
;             const unsigned tg = og / nx;
;             if (og + 1u == (tg + 1u) * nx) xb_add(&bar[XB_TOPGEN], 1u);
;             else XB_SPIN(xb_ld(&bar[XB_TOPGEN]) == tg, bar);
;             __builtin_amdgcn_fence(__ATOMIC_ACQUIRE, "agent");
;             xb_add(&bar[XB_XGEN(b.x)], 1u);
;             asm volatile("s_waitcnt vmcnt(0)" ::: "memory");
;         } else {
;             XB_SPIN(xb_ld(&bar[XB_XGEN(b.x)]) == gen, bar);
.LBB0_363:
	s_or_b64 exec, exec, s[10:11]
	v_cvt_f32_u32_e32 v4, v2
	s_waitcnt vmcnt(0)
	v_readfirstlane_b32 s8, v3
	v_sub_u32_e32 v3, 0, v2
	v_rcp_iflag_f32_e32 v4, v4
	v_add_u32_e32 v5, s8, v1
	v_mul_f32_e32 v4, 0x4f7ffffe, v4
	v_cvt_u32_f32_e32 v4, v4
	v_mul_lo_u32 v1, v3, v4
	v_mul_hi_u32 v1, v4, v1
	v_add_u32_e32 v1, v4, v1
	v_mul_hi_u32 v1, v5, v1
	v_mul_lo_u32 v3, v1, v2
	v_sub_u32_e32 v3, v5, v3
	v_add_u32_e32 v4, 1, v1
	v_cmp_ge_u32_e32 vcc, v3, v2
	s_nop 1
	v_cndmask_b32_e32 v1, v1, v4, vcc
	v_sub_u32_e32 v4, v3, v2
	v_cndmask_b32_e32 v3, v3, v4, vcc
	v_add_u32_e32 v4, 1, v1
	v_cmp_ge_u32_e32 vcc, v3, v2
	v_add_u32_e32 v3, 1, v5
	s_nop 0
	v_cndmask_b32_e32 v1, v1, v4, vcc
	v_mul_lo_u32 v4, v2, v1
	v_add_u32_e32 v2, v4, v2
	v_cmp_ne_u32_e32 vcc, v3, v2
	s_and_saveexec_b64 s[8:9], vcc
	s_xor_b64 s[8:9], exec, s[8:9]
	s_cbranch_execz .LBB0_377
	buffer_inv sc1
	s_waitcnt lgkmcnt(0)
	v_add_u32_e32 v1, 1, v1
	v_mul_lo_u32 v1, v1, v0
	v_mov_b32_e32 v0, 0x3000
	global_load_dword v0, v0, s[76:77] offset:1024 sc1
	s_add_u32 s12, s76, 0x3400
	s_addc_u32 s13, s77, 0
	s_waitcnt vmcnt(0)
	v_cmp_lt_u32_e32 vcc, v0, v1
	s_and_saveexec_b64 s[10:11], vcc
	s_cbranch_execz .LBB0_376
	s_mov_b32 s24, 1
	s_mov_b64 s[14:15], 0
	v_mov_b32_e32 v0, 0
	s_branch .LBB0_367

; __device__ __forceinline__ unsigned xb_ld(unsigned* p)              { return __hip_atomic_load(p, __ATOMIC_RELAXED, __HIP_MEMORY_SCOPE_AGENT); }
; #define XB_SPIN(cond, bar) do { unsigned _sp = 0; while (cond) { __builtin_amdgcn_s_sleep(1); \
;     if ((++_sp & 255u) == 0u) { if (xb_ld(&(bar)[XB_TMO])) break; if (_sp > XB_SPIN_CAP) { atomicAdd(&(bar)[XB_TMO], 1u); break; } } } } while (0)
; __device__ __forceinline__ void xcd_barrier(const XcdBarrier& b, bool leader) {
;     ...
;         } else {
;             XB_SPIN(xb_ld(&bar[XB_XGEN(b.x)]) == gen, bar);
.LBB0_371:
	global_load_dword v2, v0, s[12:13] sc1
	s_add_i32 s24, s24, 1
	s_mov_b64 s[20:21], -1
	s_waitcnt vmcnt(0)
	v_cmp_ge_u32_e32 vcc, v2, v1
	s_orn2_b64 s[18:19], vcc, exec
	s_branch .LBB0_366

; __device__ __forceinline__ unsigned xb_ld(unsigned* p)              { return __hip_atomic_load(p, __ATOMIC_RELAXED, __HIP_MEMORY_SCOPE_AGENT); }
; __device__ __forceinline__ unsigned xb_add(unsigned* p, unsigned v) { return __hip_atomic_fetch_add(p, v, __ATOMIC_RELAXED, __HIP_MEMORY_SCOPE_AGENT); }
; #define XB_SPIN(cond, bar) do { unsigned _sp = 0; while (cond) { __builtin_amdgcn_s_sleep(1); \
;     if ((++_sp & 255u) == 0u) { if (xb_ld(&(bar)[XB_TMO])) break; if (_sp > XB_SPIN_CAP) { atomicAdd(&(bar)[XB_TMO], 1u); break; } } } } while (0)
; __device__ __forceinline__ void xcd_barrier(const XcdBarrier& b, bool leader) {
;     ...
;             __builtin_amdgcn_fence(__ATOMIC_RELEASE, "agent");
;             asm volatile("s_waitcnt vmcnt(0)" ::: "memory");
;             const unsigned og = xb_add(&bar[XB_TOP], 1u);
;             const unsigned tg = og / nx;
;             if (og + 1u == (tg + 1u) * nx) xb_add(&bar[XB_TOPGEN], 1u);
;             else XB_SPIN(xb_ld(&bar[XB_TOPGEN]) == tg, bar);
.LBB0_380:
	s_or_b64 exec, exec, s[10:11]
	buffer_inv sc1
	v_cvt_f32_u32_e32 v3, v0
	s_waitcnt vmcnt(0)
	v_readfirstlane_b32 s8, v2
	s_add_u32 s10, s76, 0x3500
	s_addc_u32 s11, s77, 0
	v_rcp_iflag_f32_e32 v3, v3
	v_add_u32_e32 v1, s8, v1
	v_add_u32_e32 v4, 1, v1
	s_mov_b64 s[12:13], -1
	v_mul_f32_e32 v2, 0x4f7ffffe, v3
	v_cvt_u32_f32_e32 v2, v2
	v_sub_u32_e32 v3, 0, v0
	v_mul_lo_u32 v3, v3, v2
	v_mul_hi_u32 v3, v2, v3
	v_add_u32_e32 v2, v2, v3
	v_mul_hi_u32 v2, v1, v2
	v_mul_lo_u32 v3, v2, v0
	v_sub_u32_e32 v1, v1, v3
	v_add_u32_e32 v5, 1, v2
	v_cmp_ge_u32_e32 vcc, v1, v0
	v_sub_u32_e32 v3, v1, v0
	s_nop 0
	v_cndmask_b32_e32 v2, v2, v5, vcc
	v_cndmask_b32_e32 v1, v1, v3, vcc
	v_add_u32_e32 v3, 1, v2
	v_cmp_ge_u32_e32 vcc, v1, v0
	s_nop 1
	v_cndmask_b32_e32 v2, v2, v3, vcc
	v_mul_lo_u32 v1, v0, v2
	v_add_u32_e32 v0, v1, v0
	v_mov_b32_e32 v2, v0
	v_cmp_ne_u32_e32 vcc, v4, v0
	v_mov_b64_e32 v[0:1], s[10:11]
	s_and_saveexec_b64 s[8:9], vcc
	s_cbranch_execz .LBB0_392
	v_mov_b32_e32 v0, 0
	global_load_dword v1, v0, s[10:11] offset:-256 sc1
	s_mov_b64 s[16:17], 0
	s_waitcnt vmcnt(0)
	v_cmp_lt_u32_e32 vcc, v1, v2
	s_and_saveexec_b64 s[14:15], vcc
	s_cbranch_execz .LBB0_391
	s_add_u32 s12, s76, 0x200
	s_addc_u32 s13, s77, 0
	s_mov_b32 s26, 1
	s_branch .LBB0_384

; __device__ __forceinline__ unsigned xb_ld(unsigned* p)              { return __hip_atomic_load(p, __ATOMIC_RELAXED, __HIP_MEMORY_SCOPE_AGENT); }
; __device__ __forceinline__ unsigned xb_add(unsigned* p, unsigned v) { return __hip_atomic_fetch_add(p, v, __ATOMIC_RELAXED, __HIP_MEMORY_SCOPE_AGENT); }
; #define XB_SPIN(cond, bar) do { unsigned _sp = 0; while (cond) { __builtin_amdgcn_s_sleep(1); \
;     if ((++_sp & 255u) == 0u) { if (xb_ld(&(bar)[XB_TMO])) break; if (_sp > XB_SPIN_CAP) { atomicAdd(&(bar)[XB_TMO], 1u); break; } } } } while (0)
; __device__ __forceinline__ void xcd_barrier(const XcdBarrier& b, bool leader) {
;     ...
;             const unsigned og = xb_add(&bar[XB_TOP], 1u);
;             const unsigned tg = og / nx;
;             if (og + 1u == (tg + 1u) * nx) xb_add(&bar[XB_TOPGEN], 1u);
;             else XB_SPIN(xb_ld(&bar[XB_TOPGEN]) == tg, bar);
.LBB0_388:
	global_load_dword v1, v0, s[10:11] offset:-256 sc1
	s_add_i32 s26, s26, 1
	s_mov_b64 s[20:21], -1
	s_waitcnt vmcnt(0)
	v_cmp_ge_u32_e32 vcc, v1, v2
	s_orn2_b64 s[24:25], vcc, exec
	s_branch .LBB0_383

; __device__ __forceinline__ unsigned xb_ld(unsigned* p)              { return __hip_atomic_load(p, __ATOMIC_RELAXED, __HIP_MEMORY_SCOPE_AGENT); }
; __device__ __forceinline__ unsigned xb_add(unsigned* p, unsigned v) { return __hip_atomic_fetch_add(p, v, __ATOMIC_RELAXED, __HIP_MEMORY_SCOPE_AGENT); }
; #define XB_SPIN(cond, bar) do { unsigned _sp = 0; while (cond) { __builtin_amdgcn_s_sleep(1); \
;     if ((++_sp & 255u) == 0u) { if (xb_ld(&(bar)[XB_TMO])) break; if (_sp > XB_SPIN_CAP) { atomicAdd(&(bar)[XB_TMO], 1u); break; } } } } while (0)
; __device__ __forceinline__ void xcd_barrier(const XcdBarrier& b, bool leader) {
;     ...
;         const unsigned old = xb_add(&bar[XB_XSUB(b.x)], 1u);
;         const unsigned gen = old / nloc;
;         if (old + 1u == (gen + 1u) * nloc) {
;             __builtin_amdgcn_fence(__ATOMIC_RELEASE, "agent");
;             asm volatile("s_waitcnt vmcnt(0)" ::: "memory");
;             const unsigned og = xb_add(&bar[XB_TOP], 1u);
;             const unsigned tg = og / nx;
;             if (og + 1u == (tg + 1u) * nx) xb_add(&bar[XB_TOPGEN], 1u);
;             else XB_SPIN(xb_ld(&bar[XB_TOPGEN]) == tg, bar);
;             __builtin_amdgcn_fence(__ATOMIC_ACQUIRE, "agent");
;             xb_add(&bar[XB_XGEN(b.x)], 1u);
;             asm volatile("s_waitcnt vmcnt(0)" ::: "memory");
;         } else {
;             XB_SPIN(xb_ld(&bar[XB_XGEN(b.x)]) == gen, bar);
.LBB0_1428:
	s_or_b64 exec, exec, s[10:11]
	v_cvt_f32_u32_e32 v4, v2
	s_waitcnt vmcnt(0)
	v_readfirstlane_b32 s3, v3
	v_sub_u32_e32 v3, 0, v2
	v_rcp_iflag_f32_e32 v4, v4
	v_add_u32_e32 v5, s3, v1
	v_mul_f32_e32 v4, 0x4f7ffffe, v4
	v_cvt_u32_f32_e32 v4, v4
	v_mul_lo_u32 v1, v3, v4
	v_mul_hi_u32 v1, v4, v1
	v_add_u32_e32 v1, v4, v1
	v_mul_hi_u32 v1, v5, v1
	v_mul_lo_u32 v3, v1, v2
	v_sub_u32_e32 v3, v5, v3
	v_add_u32_e32 v4, 1, v1
	v_cmp_ge_u32_e32 vcc, v3, v2
	s_nop 1
	v_cndmask_b32_e32 v1, v1, v4, vcc
	v_sub_u32_e32 v4, v3, v2
	v_cndmask_b32_e32 v3, v3, v4, vcc
	v_add_u32_e32 v4, 1, v1
	v_cmp_ge_u32_e32 vcc, v3, v2
	v_add_u32_e32 v3, 1, v5
	s_nop 0
	v_cndmask_b32_e32 v1, v1, v4, vcc
	v_mul_lo_u32 v4, v2, v1
	v_add_u32_e32 v2, v4, v2
	v_cmp_ne_u32_e32 vcc, v3, v2
	s_and_saveexec_b64 s[8:9], vcc
	s_xor_b64 s[8:9], exec, s[8:9]
	s_cbranch_execz .LBB0_1446
	buffer_inv sc1
	s_waitcnt lgkmcnt(0)
	v_add_u32_e32 v1, 1, v1
	v_mul_lo_u32 v1, v1, v0
	v_mov_b32_e32 v0, 0x3000
	global_load_dword v0, v0, s[76:77] offset:1024 sc1
	s_add_u32 s12, s76, 0x3400
	s_addc_u32 s13, s77, 0
	s_waitcnt vmcnt(0)
	v_cmp_lt_u32_e32 vcc, v0, v1
	s_and_saveexec_b64 s[10:11], vcc
	s_cbranch_execz .LBB0_1445
	s_mov_b32 s3, 1
	s_mov_b64 s[14:15], 0
	v_mov_b32_e32 v0, 0
	s_branch .LBB0_1432

; __device__ __forceinline__ unsigned xb_ld(unsigned* p)              { return __hip_atomic_load(p, __ATOMIC_RELAXED, __HIP_MEMORY_SCOPE_AGENT); }
; #define XB_SPIN(cond, bar) do { unsigned _sp = 0; while (cond) { __builtin_amdgcn_s_sleep(1); \
;     if ((++_sp & 255u) == 0u) { if (xb_ld(&(bar)[XB_TMO])) break; if (_sp > XB_SPIN_CAP) { atomicAdd(&(bar)[XB_TMO], 1u); break; } } } } while (0)
; __device__ __forceinline__ void xcd_barrier(const XcdBarrier& b, bool leader) {
;     ...
;         } else {
;             XB_SPIN(xb_ld(&bar[XB_XGEN(b.x)]) == gen, bar);
.LBB0_1436:
	global_load_dword v2, v0, s[12:13] sc1
	s_add_i32 s3, s3, 1
	s_mov_b64 s[20:21], -1
	s_waitcnt vmcnt(0)
	v_cmp_ge_u32_e32 vcc, v2, v1
	s_orn2_b64 s[18:19], vcc, exec
	s_branch .LBB0_1431

; __device__ __forceinline__ unsigned xb_ld(unsigned* p)              { return __hip_atomic_load(p, __ATOMIC_RELAXED, __HIP_MEMORY_SCOPE_AGENT); }
; __device__ __forceinline__ unsigned xb_add(unsigned* p, unsigned v) { return __hip_atomic_fetch_add(p, v, __ATOMIC_RELAXED, __HIP_MEMORY_SCOPE_AGENT); }
; #define XB_SPIN(cond, bar) do { unsigned _sp = 0; while (cond) { __builtin_amdgcn_s_sleep(1); \
;     if ((++_sp & 255u) == 0u) { if (xb_ld(&(bar)[XB_TMO])) break; if (_sp > XB_SPIN_CAP) { atomicAdd(&(bar)[XB_TMO], 1u); break; } } } } while (0)
; __device__ __forceinline__ void xcd_barrier(const XcdBarrier& b, bool leader) {
;     ...
;             __builtin_amdgcn_fence(__ATOMIC_RELEASE, "agent");
;             asm volatile("s_waitcnt vmcnt(0)" ::: "memory");
;             const unsigned og = xb_add(&bar[XB_TOP], 1u);
;             const unsigned tg = og / nx;
;             if (og + 1u == (tg + 1u) * nx) xb_add(&bar[XB_TOPGEN], 1u);
;             else XB_SPIN(xb_ld(&bar[XB_TOPGEN]) == tg, bar);
.LBB0_1449:
	s_or_b64 exec, exec, s[10:11]
	buffer_inv sc1
	v_cvt_f32_u32_e32 v3, v0
	s_waitcnt vmcnt(0)
	v_readfirstlane_b32 s3, v2
	s_add_u32 s10, s76, 0x3500
	s_addc_u32 s11, s77, 0
	v_rcp_iflag_f32_e32 v3, v3
	v_add_u32_e32 v1, s3, v1
	v_add_u32_e32 v4, 1, v1
	s_mov_b64 s[12:13], -1
	v_mul_f32_e32 v2, 0x4f7ffffe, v3
	v_cvt_u32_f32_e32 v2, v2
	v_sub_u32_e32 v3, 0, v0
	v_mul_lo_u32 v3, v3, v2
	v_mul_hi_u32 v3, v2, v3
	v_add_u32_e32 v2, v2, v3
	v_mul_hi_u32 v2, v1, v2
	v_mul_lo_u32 v3, v2, v0
	v_sub_u32_e32 v1, v1, v3
	v_add_u32_e32 v5, 1, v2
	v_cmp_ge_u32_e32 vcc, v1, v0
	v_sub_u32_e32 v3, v1, v0
	s_nop 0
	v_cndmask_b32_e32 v2, v2, v5, vcc
	v_cndmask_b32_e32 v1, v1, v3, vcc
	v_add_u32_e32 v3, 1, v2
	v_cmp_ge_u32_e32 vcc, v1, v0
	s_nop 1
	v_cndmask_b32_e32 v2, v2, v3, vcc
	v_mul_lo_u32 v1, v0, v2
	v_add_u32_e32 v0, v1, v0
	v_mov_b32_e32 v2, v0
	v_cmp_ne_u32_e32 vcc, v4, v0
	v_mov_b64_e32 v[0:1], s[10:11]
	s_and_saveexec_b64 s[8:9], vcc
	s_cbranch_execz .LBB0_1461
	v_mov_b32_e32 v0, 0
	global_load_dword v1, v0, s[10:11] offset:-256 sc1
	s_mov_b64 s[16:17], 0
	s_waitcnt vmcnt(0)
	v_cmp_lt_u32_e32 vcc, v1, v2
	s_and_saveexec_b64 s[14:15], vcc
	s_cbranch_execz .LBB0_1460
	s_add_u32 s12, s76, 0x200
	s_addc_u32 s13, s77, 0
	s_mov_b32 s3, 1
	s_branch .LBB0_1453

; __device__ __forceinline__ unsigned xb_ld(unsigned* p)              { return __hip_atomic_load(p, __ATOMIC_RELAXED, __HIP_MEMORY_SCOPE_AGENT); }
; __device__ __forceinline__ unsigned xb_add(unsigned* p, unsigned v) { return __hip_atomic_fetch_add(p, v, __ATOMIC_RELAXED, __HIP_MEMORY_SCOPE_AGENT); }
; #define XB_SPIN(cond, bar) do { unsigned _sp = 0; while (cond) { __builtin_amdgcn_s_sleep(1); \
;     if ((++_sp & 255u) == 0u) { if (xb_ld(&(bar)[XB_TMO])) break; if (_sp > XB_SPIN_CAP) { atomicAdd(&(bar)[XB_TMO], 1u); break; } } } } while (0)
; __device__ __forceinline__ void xcd_barrier(const XcdBarrier& b, bool leader) {
;     ...
;             const unsigned og = xb_add(&bar[XB_TOP], 1u);
;             const unsigned tg = og / nx;
;             if (og + 1u == (tg + 1u) * nx) xb_add(&bar[XB_TOPGEN], 1u);
;             else XB_SPIN(xb_ld(&bar[XB_TOPGEN]) == tg, bar);
.LBB0_1457:
	global_load_dword v1, v0, s[10:11] offset:-256 sc1
	s_add_i32 s3, s3, 1
	s_mov_b64 s[20:21], -1
	s_waitcnt vmcnt(0)
	v_cmp_ge_u32_e32 vcc, v1, v2
	s_orn2_b64 s[24:25], vcc, exec
	s_branch .LBB0_1452

; __device__ __forceinline__ unsigned xb_ld(unsigned* p)              { return __hip_atomic_load(p, __ATOMIC_RELAXED, __HIP_MEMORY_SCOPE_AGENT); }
; __device__ __forceinline__ unsigned xb_add(unsigned* p, unsigned v) { return __hip_atomic_fetch_add(p, v, __ATOMIC_RELAXED, __HIP_MEMORY_SCOPE_AGENT); }
; #define XB_SPIN(cond, bar) do { unsigned _sp = 0; while (cond) { __builtin_amdgcn_s_sleep(1); \
;     if ((++_sp & 255u) == 0u) { if (xb_ld(&(bar)[XB_TMO])) break; if (_sp > XB_SPIN_CAP) { atomicAdd(&(bar)[XB_TMO], 1u); break; } } } } while (0)
; __device__ __forceinline__ void xcd_barrier(const XcdBarrier& b, bool leader) {
;     ...
;         const unsigned old = xb_add(&bar[XB_XSUB(b.x)], 1u);
;         const unsigned gen = old / nloc;
;         if (old + 1u == (gen + 1u) * nloc) {
;             __builtin_amdgcn_fence(__ATOMIC_RELEASE, "agent");
;             asm volatile("s_waitcnt vmcnt(0)" ::: "memory");
;             const unsigned og = xb_add(&bar[XB_TOP], 1u);
;             const unsigned tg = og / nx;
;             if (og + 1u == (tg + 1u) * nx) xb_add(&bar[XB_TOPGEN], 1u);
;             else XB_SPIN(xb_ld(&bar[XB_TOPGEN]) == tg, bar);
;             __builtin_amdgcn_fence(__ATOMIC_ACQUIRE, "agent");
;             xb_add(&bar[XB_XGEN(b.x)], 1u);
;             asm volatile("s_waitcnt vmcnt(0)" ::: "memory");
;         } else {
;             XB_SPIN(xb_ld(&bar[XB_XGEN(b.x)]) == gen, bar);
.LBB0_2150:
	s_or_b64 exec, exec, s[12:13]
	v_cvt_f32_u32_e32 v4, v2
	s_waitcnt vmcnt(0)
	v_readfirstlane_b32 s3, v3
	v_sub_u32_e32 v3, 0, v2
	v_rcp_iflag_f32_e32 v4, v4
	v_add_u32_e32 v5, s3, v1
	v_mul_f32_e32 v4, 0x4f7ffffe, v4
	v_cvt_u32_f32_e32 v4, v4
	v_mul_lo_u32 v1, v3, v4
	v_mul_hi_u32 v1, v4, v1
	v_add_u32_e32 v1, v4, v1
	v_mul_hi_u32 v1, v5, v1
	v_mul_lo_u32 v3, v1, v2
	v_sub_u32_e32 v3, v5, v3
	v_add_u32_e32 v4, 1, v1
	v_cmp_ge_u32_e32 vcc, v3, v2
	s_nop 1
	v_cndmask_b32_e32 v1, v1, v4, vcc
	v_sub_u32_e32 v4, v3, v2
	v_cndmask_b32_e32 v3, v3, v4, vcc
	v_add_u32_e32 v4, 1, v1
	v_cmp_ge_u32_e32 vcc, v3, v2
	v_add_u32_e32 v3, 1, v5
	s_nop 0
	v_cndmask_b32_e32 v1, v1, v4, vcc
	v_mul_lo_u32 v4, v2, v1
	v_add_u32_e32 v2, v4, v2
	v_cmp_ne_u32_e32 vcc, v3, v2
	s_and_saveexec_b64 s[10:11], vcc
	s_xor_b64 s[10:11], exec, s[10:11]
	s_cbranch_execz .LBB0_2164
	buffer_inv sc1
	s_waitcnt lgkmcnt(0)
	v_add_u32_e32 v1, 1, v1
	v_mul_lo_u32 v1, v1, v0
	v_mov_b32_e32 v0, 0x3000
	global_load_dword v0, v0, s[76:77] offset:1024 sc1
	s_add_u32 s14, s76, 0x3400
	s_addc_u32 s15, s77, 0
	s_waitcnt vmcnt(0)
	v_cmp_lt_u32_e32 vcc, v0, v1
	s_and_saveexec_b64 s[12:13], vcc
	s_cbranch_execz .LBB0_2163
	s_mov_b32 s3, 1
	s_mov_b64 s[16:17], 0
	v_mov_b32_e32 v0, 0
	s_branch .LBB0_2154

; __device__ __forceinline__ unsigned xb_ld(unsigned* p)              { return __hip_atomic_load(p, __ATOMIC_RELAXED, __HIP_MEMORY_SCOPE_AGENT); }
; #define XB_SPIN(cond, bar) do { unsigned _sp = 0; while (cond) { __builtin_amdgcn_s_sleep(1); \
;     if ((++_sp & 255u) == 0u) { if (xb_ld(&(bar)[XB_TMO])) break; if (_sp > XB_SPIN_CAP) { atomicAdd(&(bar)[XB_TMO], 1u); break; } } } } while (0)
; __device__ __forceinline__ void xcd_barrier(const XcdBarrier& b, bool leader) {
;     ...
;         } else {
;             XB_SPIN(xb_ld(&bar[XB_XGEN(b.x)]) == gen, bar);
.LBB0_2158:
	global_load_dword v2, v0, s[14:15] sc1
	s_add_i32 s3, s3, 1
	s_mov_b64 s[22:23], -1
	s_waitcnt vmcnt(0)
	v_cmp_ge_u32_e32 vcc, v2, v1
	s_orn2_b64 s[20:21], vcc, exec
	s_branch .LBB0_2153

; __device__ __forceinline__ unsigned xb_ld(unsigned* p)              { return __hip_atomic_load(p, __ATOMIC_RELAXED, __HIP_MEMORY_SCOPE_AGENT); }
; __device__ __forceinline__ unsigned xb_add(unsigned* p, unsigned v) { return __hip_atomic_fetch_add(p, v, __ATOMIC_RELAXED, __HIP_MEMORY_SCOPE_AGENT); }
; #define XB_SPIN(cond, bar) do { unsigned _sp = 0; while (cond) { __builtin_amdgcn_s_sleep(1); \
;     if ((++_sp & 255u) == 0u) { if (xb_ld(&(bar)[XB_TMO])) break; if (_sp > XB_SPIN_CAP) { atomicAdd(&(bar)[XB_TMO], 1u); break; } } } } while (0)
; __device__ __forceinline__ void xcd_barrier(const XcdBarrier& b, bool leader) {
;     ...
;             __builtin_amdgcn_fence(__ATOMIC_RELEASE, "agent");
;             asm volatile("s_waitcnt vmcnt(0)" ::: "memory");
;             const unsigned og = xb_add(&bar[XB_TOP], 1u);
;             const unsigned tg = og / nx;
;             if (og + 1u == (tg + 1u) * nx) xb_add(&bar[XB_TOPGEN], 1u);
;             else XB_SPIN(xb_ld(&bar[XB_TOPGEN]) == tg, bar);
.LBB0_2167:
	s_or_b64 exec, exec, s[12:13]
	buffer_inv sc1
	v_cvt_f32_u32_e32 v3, v0
	s_waitcnt vmcnt(0)
	v_readfirstlane_b32 s3, v2
	s_add_u32 s12, s76, 0x3500
	s_addc_u32 s13, s77, 0
	v_rcp_iflag_f32_e32 v3, v3
	v_add_u32_e32 v1, s3, v1
	v_add_u32_e32 v4, 1, v1
	s_mov_b64 s[14:15], -1
	v_mul_f32_e32 v2, 0x4f7ffffe, v3
	v_cvt_u32_f32_e32 v2, v2
	v_sub_u32_e32 v3, 0, v0
	v_mul_lo_u32 v3, v3, v2
	v_mul_hi_u32 v3, v2, v3
	v_add_u32_e32 v2, v2, v3
	v_mul_hi_u32 v2, v1, v2
	v_mul_lo_u32 v3, v2, v0
	v_sub_u32_e32 v1, v1, v3
	v_add_u32_e32 v5, 1, v2
	v_cmp_ge_u32_e32 vcc, v1, v0
	v_sub_u32_e32 v3, v1, v0
	s_nop 0
	v_cndmask_b32_e32 v2, v2, v5, vcc
	v_cndmask_b32_e32 v1, v1, v3, vcc
	v_add_u32_e32 v3, 1, v2
	v_cmp_ge_u32_e32 vcc, v1, v0
	s_nop 1
	v_cndmask_b32_e32 v2, v2, v3, vcc
	v_mul_lo_u32 v1, v0, v2
	v_add_u32_e32 v0, v1, v0
	v_mov_b32_e32 v2, v0
	v_cmp_ne_u32_e32 vcc, v4, v0
	v_mov_b64_e32 v[0:1], s[12:13]
	s_and_saveexec_b64 s[10:11], vcc
	s_cbranch_execz .LBB0_2179
	v_mov_b32_e32 v0, 0
	global_load_dword v1, v0, s[12:13] offset:-256 sc1
	s_mov_b64 s[18:19], 0
	s_waitcnt vmcnt(0)
	v_cmp_lt_u32_e32 vcc, v1, v2
	s_and_saveexec_b64 s[16:17], vcc
	s_cbranch_execz .LBB0_2178
	s_add_u32 s14, s76, 0x200
	s_addc_u32 s15, s77, 0
	s_mov_b32 s3, 1
	s_branch .LBB0_2171

; __device__ __forceinline__ unsigned xb_ld(unsigned* p)              { return __hip_atomic_load(p, __ATOMIC_RELAXED, __HIP_MEMORY_SCOPE_AGENT); }
; __device__ __forceinline__ unsigned xb_add(unsigned* p, unsigned v) { return __hip_atomic_fetch_add(p, v, __ATOMIC_RELAXED, __HIP_MEMORY_SCOPE_AGENT); }
; #define XB_SPIN(cond, bar) do { unsigned _sp = 0; while (cond) { __builtin_amdgcn_s_sleep(1); \
;     if ((++_sp & 255u) == 0u) { if (xb_ld(&(bar)[XB_TMO])) break; if (_sp > XB_SPIN_CAP) { atomicAdd(&(bar)[XB_TMO], 1u); break; } } } } while (0)
; __device__ __forceinline__ void xcd_barrier(const XcdBarrier& b, bool leader) {
;     ...
;             const unsigned og = xb_add(&bar[XB_TOP], 1u);
;             const unsigned tg = og / nx;
;             if (og + 1u == (tg + 1u) * nx) xb_add(&bar[XB_TOPGEN], 1u);
;             else XB_SPIN(xb_ld(&bar[XB_TOPGEN]) == tg, bar);
.LBB0_2175:
	global_load_dword v1, v0, s[12:13] offset:-256 sc1
	s_add_i32 s3, s3, 1
	s_mov_b64 s[22:23], -1
	s_waitcnt vmcnt(0)
	v_cmp_ge_u32_e32 vcc, v1, v2
	s_orn2_b64 s[26:27], vcc, exec
	s_branch .LBB0_2170

; __device__ __forceinline__ unsigned xb_ld(unsigned* p)              { return __hip_atomic_load(p, __ATOMIC_RELAXED, __HIP_MEMORY_SCOPE_AGENT); }
; __device__ __forceinline__ unsigned xb_add(unsigned* p, unsigned v) { return __hip_atomic_fetch_add(p, v, __ATOMIC_RELAXED, __HIP_MEMORY_SCOPE_AGENT); }
; #define XB_SPIN(cond, bar) do { unsigned _sp = 0; while (cond) { __builtin_amdgcn_s_sleep(1); \
;     if ((++_sp & 255u) == 0u) { if (xb_ld(&(bar)[XB_TMO])) break; if (_sp > XB_SPIN_CAP) { atomicAdd(&(bar)[XB_TMO], 1u); break; } } } } while (0)
; __device__ __forceinline__ void xcd_barrier(const XcdBarrier& b, bool leader) {
;     ...
;         const unsigned old = xb_add(&bar[XB_XSUB(b.x)], 1u);
;         const unsigned gen = old / nloc;
;         if (old + 1u == (gen + 1u) * nloc) {
;             __builtin_amdgcn_fence(__ATOMIC_RELEASE, "agent");
;             asm volatile("s_waitcnt vmcnt(0)" ::: "memory");
;             const unsigned og = xb_add(&bar[XB_TOP], 1u);
;             const unsigned tg = og / nx;
;             if (og + 1u == (tg + 1u) * nx) xb_add(&bar[XB_TOPGEN], 1u);
;             else XB_SPIN(xb_ld(&bar[XB_TOPGEN]) == tg, bar);
;             __builtin_amdgcn_fence(__ATOMIC_ACQUIRE, "agent");
;             xb_add(&bar[XB_XGEN(b.x)], 1u);
;             asm volatile("s_waitcnt vmcnt(0)" ::: "memory");
;         } else {
;             XB_SPIN(xb_ld(&bar[XB_XGEN(b.x)]) == gen, bar);
.LBB0_2386:
	s_or_b64 exec, exec, s[10:11]
	v_cvt_f32_u32_e32 v4, v2
	s_waitcnt vmcnt(0)
	v_readfirstlane_b32 s6, v3
	v_sub_u32_e32 v3, 0, v2
	v_rcp_iflag_f32_e32 v4, v4
	v_add_u32_e32 v5, s6, v1
	v_mul_f32_e32 v4, 0x4f7ffffe, v4
	v_cvt_u32_f32_e32 v4, v4
	v_mul_lo_u32 v1, v3, v4
	v_mul_hi_u32 v1, v4, v1
	v_add_u32_e32 v1, v4, v1
	v_mul_hi_u32 v1, v5, v1
	v_mul_lo_u32 v3, v1, v2
	v_sub_u32_e32 v3, v5, v3
	v_add_u32_e32 v4, 1, v1
	v_cmp_ge_u32_e32 vcc, v3, v2
	s_nop 1
	v_cndmask_b32_e32 v1, v1, v4, vcc
	v_sub_u32_e32 v4, v3, v2
	v_cndmask_b32_e32 v3, v3, v4, vcc
	v_add_u32_e32 v4, 1, v1
	v_cmp_ge_u32_e32 vcc, v3, v2
	v_add_u32_e32 v3, 1, v5
	s_nop 0
	v_cndmask_b32_e32 v1, v1, v4, vcc
	v_mul_lo_u32 v4, v2, v1
	v_add_u32_e32 v2, v4, v2
	v_cmp_ne_u32_e32 vcc, v3, v2
	s_and_saveexec_b64 s[6:7], vcc
	s_xor_b64 s[6:7], exec, s[6:7]
	s_cbranch_execz .LBB0_2400
	buffer_inv sc1
	s_waitcnt lgkmcnt(0)
	v_add_u32_e32 v1, 1, v1
	v_mul_lo_u32 v1, v1, v0
	v_mov_b32_e32 v0, 0x3000
	global_load_dword v0, v0, s[76:77] offset:1024 sc1
	s_add_u32 s12, s76, 0x3400
	s_addc_u32 s13, s77, 0
	s_waitcnt vmcnt(0)
	v_cmp_lt_u32_e32 vcc, v0, v1
	s_and_saveexec_b64 s[10:11], vcc
	s_cbranch_execz .LBB0_2399
	s_mov_b32 s24, 1
	s_mov_b64 s[14:15], 0
	v_mov_b32_e32 v0, 0
	s_branch .LBB0_2390

; __device__ __forceinline__ unsigned xb_ld(unsigned* p)              { return __hip_atomic_load(p, __ATOMIC_RELAXED, __HIP_MEMORY_SCOPE_AGENT); }
; __device__ __forceinline__ unsigned xb_add(unsigned* p, unsigned v) { return __hip_atomic_fetch_add(p, v, __ATOMIC_RELAXED, __HIP_MEMORY_SCOPE_AGENT); }
; #define XB_SPIN(cond, bar) do { unsigned _sp = 0; while (cond) { __builtin_amdgcn_s_sleep(1); \
;     if ((++_sp & 255u) == 0u) { if (xb_ld(&(bar)[XB_TMO])) break; if (_sp > XB_SPIN_CAP) { atomicAdd(&(bar)[XB_TMO], 1u); break; } } } } while (0)
; __device__ __forceinline__ void xcd_barrier(const XcdBarrier& b, bool leader) {
;     ...
;             __builtin_amdgcn_fence(__ATOMIC_RELEASE, "agent");
;             asm volatile("s_waitcnt vmcnt(0)" ::: "memory");
;             const unsigned og = xb_add(&bar[XB_TOP], 1u);
;             const unsigned tg = og / nx;
;             if (og + 1u == (tg + 1u) * nx) xb_add(&bar[XB_TOPGEN], 1u);
;             else XB_SPIN(xb_ld(&bar[XB_TOPGEN]) == tg, bar);
.LBB0_2403:
	s_or_b64 exec, exec, s[10:11]
	buffer_inv sc1
	v_cvt_f32_u32_e32 v3, v0
	s_waitcnt vmcnt(0)
	v_readfirstlane_b32 s6, v2
	s_add_u32 s10, s76, 0x3500
	s_addc_u32 s11, s77, 0
	v_rcp_iflag_f32_e32 v3, v3
	v_add_u32_e32 v1, s6, v1
	v_add_u32_e32 v4, 1, v1
	s_mov_b64 s[12:13], -1
	v_mul_f32_e32 v2, 0x4f7ffffe, v3
	v_cvt_u32_f32_e32 v2, v2
	v_sub_u32_e32 v3, 0, v0
	v_mul_lo_u32 v3, v3, v2
	v_mul_hi_u32 v3, v2, v3
	v_add_u32_e32 v2, v2, v3
	v_mul_hi_u32 v2, v1, v2
	v_mul_lo_u32 v3, v2, v0
	v_sub_u32_e32 v1, v1, v3
	v_add_u32_e32 v5, 1, v2
	v_cmp_ge_u32_e32 vcc, v1, v0
	v_sub_u32_e32 v3, v1, v0
	s_nop 0
	v_cndmask_b32_e32 v2, v2, v5, vcc
	v_cndmask_b32_e32 v1, v1, v3, vcc
	v_add_u32_e32 v3, 1, v2
	v_cmp_ge_u32_e32 vcc, v1, v0
	s_nop 1
	v_cndmask_b32_e32 v2, v2, v3, vcc
	v_mul_lo_u32 v1, v0, v2
	v_add_u32_e32 v0, v1, v0
	v_mov_b32_e32 v2, v0
	v_cmp_ne_u32_e32 vcc, v4, v0
	v_mov_b64_e32 v[0:1], s[10:11]
	s_and_saveexec_b64 s[6:7], vcc
	s_cbranch_execz .LBB0_2415
	v_mov_b32_e32 v0, 0
	global_load_dword v1, v0, s[10:11] offset:-256 sc1
	s_mov_b64 s[16:17], 0
	s_waitcnt vmcnt(0)
	v_cmp_lt_u32_e32 vcc, v1, v2
	s_and_saveexec_b64 s[14:15], vcc
	s_cbranch_execz .LBB0_2414
	s_add_u32 s12, s76, 0x200
	s_addc_u32 s13, s77, 0
	s_mov_b32 s26, 1
	s_branch .LBB0_2407
